# diff loop: K-fragment ds_read_b128 hoisted early into free VGPR quads (renamed), lgkmcnt waits re-derived
# baseline (speedup 1.0000x reference)
.LBB0_925:
	s_waitcnt lgkmcnt(3)
	v_mfma_f32_16x16x32_bf16 v[172:175], v[130:133], v[34:37], v[2:5]
	ds_read_b128 v[184:187], v247 offset:2048
	v_mfma_f32_16x16x32_bf16 v[180:183], v[130:133], v[38:41], v[10:13]
	s_nop 2
	s_nop 1
	s_nop 0
	v_exp_f32_e32 v200, v172
	v_exp_f32_e32 v201, v175
	s_waitcnt lgkmcnt(3)
	v_mfma_f32_16x16x32_bf16 v[176:179], v[168:171], v[34:37], v[2:5]
	v_exp_f32_e32 v180, v180
	ds_read_b64 v[216:217], v248 offset:37376
	ds_read_b64 v[218:219], v248 offset:37408
	v_mfma_f32_16x16x32_bf16 v[168:171], v[168:171], v[38:41], v[10:13]
	ds_read_b64 v[220:221], v248 offset:39680
	ds_read_b64 v[222:223], v248 offset:39712
	s_nop 2
	v_exp_f32_e32 v204, v176
	v_exp_f32_e32 v176, v173
	s_waitcnt lgkmcnt(6)
	v_mfma_f32_16x16x32_bf16 v[188:191], v[162:165], v[42:45], v[6:9]
	v_exp_f32_e32 v205, v177
	v_exp_f32_e32 v213, v168
	v_exp_f32_e32 v168, v181
	v_mfma_f32_16x16x32_bf16 v[196:199], v[162:165], v[46:49], v[14:17]
	v_exp_f32_e32 v181, v169
	v_exp_f32_e32 v169, v182
	v_exp_f32_e32 v182, v170
	v_exp_f32_e32 v170, v183
	v_exp_f32_e32 v171, v171
	v_exp_f32_e32 v177, v174
	v_cvt_pk_bf16_f32 v168, v180, v168
	v_cvt_pk_bf16_f32 v169, v169, v170
	v_cvt_pk_bf16_f32 v170, v213, v181
	v_cvt_pk_bf16_f32 v171, v182, v171
	ds_read_b64 v[180:181], v248 offset:32768
	ds_read_b64 v[182:183], v248 offset:32800
	ds_read_b64 v[212:213], v248 offset:35072
	ds_read_b64 v[214:215], v248 offset:35104
	ds_read_b128 v[172:175], v246 offset:6144
	v_cvt_pk_bf16_f32 v176, v200, v176
	v_cvt_pk_bf16_f32 v177, v177, v201
	s_waitcnt lgkmcnt(10)
	v_mfma_f32_16x16x32_bf16 v[200:203], v[232:235], v[34:37], v[2:5]
	v_exp_f32_e32 v231, v190
	v_exp_f32_e32 v206, v178
	v_exp_f32_e32 v179, v179
	v_mfma_f32_16x16x32_bf16 v[208:211], v[232:235], v[38:41], v[10:13]
	v_exp_f32_e32 v188, v188
	s_waitcnt lgkmcnt(9)
	v_mfma_f32_16x16x32_bf16 v[192:195], v[184:187], v[42:45], v[6:9]
	v_exp_f32_e32 v189, v189
	v_exp_f32_e32 v196, v196
	v_cvt_pk_bf16_f32 v178, v204, v205
	v_mfma_f32_16x16x32_bf16 v[184:187], v[184:187], v[46:49], v[14:17]
	v_cvt_pk_bf16_f32 v179, v206, v179
	s_nop 2
	v_exp_f32_e32 v192, v192
	v_exp_f32_e32 v193, v193
	v_mfma_f32_16x16x32_bf16 v[86:89], v[240:243], v[168:171], v[86:89]
	v_exp_f32_e32 v194, v194
	v_exp_f32_e32 v187, v187
	ds_read_b128 v[224:227], v247 offset:4096
	s_waitcnt lgkmcnt(4)
	v_mfma_f32_16x16x32_bf16 v[78:81], v[180:183], v[168:171], v[78:81]
	s_add_i32 s38, s38, 2
	s_addk_i32 s12, 0x80
	v_lshl_add_u64 v[148:149], v[148:149], 0, s[16:17]
	s_waitcnt lgkmcnt(2)
	v_mfma_f32_16x16x32_bf16 v[74:77], v[212:215], v[168:171], v[74:77]
	s_and_b64 vcc, exec, s[0:1]
	v_mfma_f32_16x16x32_bf16 v[70:73], v[216:219], v[168:171], v[70:73]
	v_mfma_f32_16x16x32_bf16 v[62:65], v[220:223], v[168:171], v[62:65]
	v_exp_f32_e32 v169, v191
	v_exp_f32_e32 v171, v195
	v_cvt_pk_bf16_f32 v168, v188, v189
	s_waitcnt lgkmcnt(1)
	v_mfma_f32_16x16x32_bf16 v[204:207], v[172:175], v[34:37], v[2:5]
	v_cvt_pk_bf16_f32 v169, v231, v169
	v_exp_f32_e32 v231, v184
	v_exp_f32_e32 v184, v197
	v_exp_f32_e32 v197, v185
	v_exp_f32_e32 v185, v198
	v_exp_f32_e32 v198, v186
	v_exp_f32_e32 v186, v199
	ds_read_b128 v[162:165], v247 offset:6144
	v_cvt_pk_bf16_f32 v170, v192, v193
	v_cvt_pk_bf16_f32 v171, v194, v171
	v_cvt_pk_bf16_f32 v184, v196, v184
	v_cvt_pk_bf16_f32 v185, v185, v186
	v_cvt_pk_bf16_f32 v186, v231, v197
	v_cvt_pk_bf16_f32 v187, v198, v187
	v_mfma_f32_16x16x32_bf16 v[172:175], v[172:175], v[38:41], v[10:13]
	v_exp_f32_e32 v196, v200
	v_exp_f32_e32 v197, v204
	v_exp_f32_e32 v198, v201
	v_mfma_f32_16x16x32_bf16 v[122:125], v[180:183], v[176:179], v[122:125]
	v_exp_f32_e32 v200, v207
	v_exp_f32_e32 v199, v203
	v_mfma_f32_16x16x32_bf16 v[102:105], v[180:183], v[168:171], v[102:105]
	v_mfma_f32_16x16x32_bf16 v[58:61], v[180:183], v[184:187], v[58:61]
	v_exp_f32_e32 v182, v205
	v_exp_f32_e32 v183, v206
	v_exp_f32_e32 v181, v202
	v_mfma_f32_16x16x32_bf16 v[126:129], v[240:243], v[176:179], v[126:129]
	v_cvt_pk_bf16_f32 v180, v196, v198
	v_cvt_pk_bf16_f32 v182, v197, v182
	v_cvt_pk_bf16_f32 v183, v183, v200
	v_mfma_f32_16x16x32_bf16 v[118:121], v[212:215], v[176:179], v[118:121]
	v_exp_f32_e32 v196, v208
	v_exp_f32_e32 v197, v172
	v_exp_f32_e32 v172, v209
	v_mfma_f32_16x16x32_bf16 v[110:113], v[216:219], v[176:179], v[110:113]
	v_exp_f32_e32 v200, v174
	v_cvt_pk_bf16_f32 v181, v181, v199
	v_exp_f32_e32 v198, v173
	v_mfma_f32_16x16x32_bf16 v[106:109], v[220:223], v[176:179], v[106:109]
	v_exp_f32_e32 v199, v210
	ds_read_b128 v[204:207], v246 offset:14336
	v_mfma_f32_16x16x32_bf16 v[114:117], v[240:243], v[168:171], v[114:117]
	v_mfma_f32_16x16x32_bf16 v[98:101], v[212:215], v[168:171], v[98:101]
	v_mfma_f32_16x16x32_bf16 v[94:97], v[216:219], v[168:171], v[94:97]
	v_mfma_f32_16x16x32_bf16 v[90:93], v[220:223], v[168:171], v[90:93]
	v_exp_f32_e32 v171, v175
	v_exp_f32_e32 v169, v211
	v_cvt_pk_bf16_f32 v168, v196, v172
	v_mfma_f32_16x16x32_bf16 v[82:85], v[240:243], v[184:187], v[82:85]
	v_cvt_pk_bf16_f32 v171, v200, v171
	v_mfma_f32_16x16x32_bf16 v[54:57], v[212:215], v[184:187], v[54:57]
	ds_read_b64 v[172:173], v248 offset:32832
	ds_read_b64 v[174:175], v248 offset:32864
	v_cvt_pk_bf16_f32 v169, v199, v169
	v_mfma_f32_16x16x32_bf16 v[50:53], v[216:219], v[184:187], v[50:53]
	v_cvt_pk_bf16_f32 v170, v197, v198
	ds_read_b64 v[196:197], v248 offset:37440
	ds_read_b64 v[198:199], v248 offset:37472
	ds_read_b64 v[200:201], v248 offset:39744
	ds_read_b64 v[202:203], v248 offset:39776
	v_mfma_f32_16x16x32_bf16 v[66:69], v[220:223], v[184:187], v[66:69]
	ds_read_b128 v[232:235], v246 offset:8192
	ds_read_b64 v[184:185], v248 offset:35136
	ds_read_b64 v[186:187], v248 offset:35168
	s_waitcnt lgkmcnt(11)
	v_mfma_f32_16x16x32_bf16 v[188:191], v[224:227], v[42:45], v[6:9]
	ds_read_b64 v[216:217], v248 offset:46592
	ds_read_b64 v[218:219], v248 offset:46624
	s_waitcnt lgkmcnt(12)
	v_mfma_f32_16x16x32_bf16 v[192:195], v[162:165], v[42:45], v[6:9]
	ds_read_b64 v[220:221], v248 offset:48896
	ds_read_b64 v[222:223], v248 offset:48928
	s_nop 1
	v_exp_f32_e32 v188, v188
	v_exp_f32_e32 v189, v189
	v_mfma_f32_16x16x32_bf16 v[224:227], v[224:227], v[46:49], v[14:17]
	v_exp_f32_e32 v190, v190
	s_nop 0
	v_exp_f32_e32 v192, v192
	v_exp_f32_e32 v193, v193
	v_mfma_f32_16x16x32_bf16 v[176:179], v[162:165], v[46:49], v[14:17]
	ds_read_b128 v[162:165], v246 offset:10240
	v_exp_f32_e32 v191, v191
	v_exp_f32_e32 v194, v194
	v_exp_f32_e32 v195, v195
	v_mfma_f32_16x16x32_bf16 v[126:129], v[240:243], v[180:183], v[126:129]
	v_cvt_pk_bf16_f32 v188, v188, v189
	v_cvt_pk_bf16_f32 v189, v190, v191
	v_cvt_pk_bf16_f32 v190, v192, v193
	v_mfma_f32_16x16x32_bf16 v[86:89], v[240:243], v[168:171], v[86:89]
	v_exp_f32_e32 v192, v224
	v_exp_f32_e32 v176, v176
	v_exp_f32_e32 v193, v225
	s_waitcnt lgkmcnt(12)
	v_mfma_f32_16x16x32_bf16 v[122:125], v[172:175], v[180:183], v[122:125]
	v_exp_f32_e32 v177, v177
	v_exp_f32_e32 v178, v178
	v_cvt_pk_bf16_f32 v191, v194, v195
	v_mfma_f32_16x16x32_bf16 v[78:81], v[172:175], v[168:171], v[78:81]
	s_waitcnt lgkmcnt(5)
	v_mfma_f32_16x16x32_bf16 v[118:121], v[184:187], v[180:183], v[118:121]
	v_mfma_f32_16x16x32_bf16 v[74:77], v[184:187], v[168:171], v[74:77]
	v_mfma_f32_16x16x32_bf16 v[110:113], v[196:199], v[180:183], v[110:113]
	v_mfma_f32_16x16x32_bf16 v[70:73], v[196:199], v[168:171], v[70:73]
	v_mfma_f32_16x16x32_bf16 v[106:109], v[200:203], v[180:183], v[106:109]
	v_exp_f32_e32 v180, v226
	v_mfma_f32_16x16x32_bf16 v[62:65], v[200:203], v[168:171], v[62:65]
	v_exp_f32_e32 v169, v227
	v_exp_f32_e32 v171, v179
	v_cvt_pk_bf16_f32 v168, v192, v193
	v_cvt_pk_bf16_f32 v170, v176, v177
	v_cvt_pk_bf16_f32 v169, v180, v169
	v_cvt_pk_bf16_f32 v171, v178, v171
	v_mfma_f32_16x16x32_bf16 v[102:105], v[172:175], v[188:191], v[102:105]
	ds_read_b128 v[224:227], v247 offset:12288
	v_mfma_f32_16x16x32_bf16 v[82:85], v[240:243], v[168:171], v[82:85]
	v_mfma_f32_16x16x32_bf16 v[58:61], v[172:175], v[168:171], v[58:61]
	v_mfma_f32_16x16x32_bf16 v[54:57], v[184:187], v[168:171], v[54:57]
	v_mfma_f32_16x16x32_bf16 v[50:53], v[196:199], v[168:171], v[50:53]
	v_mfma_f32_16x16x32_bf16 v[66:69], v[200:203], v[168:171], v[66:69]
	v_mfma_f32_16x16x32_bf16 v[176:179], v[232:235], v[34:37], v[2:5]
	s_waitcnt lgkmcnt(1)
	v_mfma_f32_16x16x32_bf16 v[180:183], v[162:165], v[34:37], v[2:5]
	s_nop 5
	v_exp_f32_e32 v176, v176
	v_mfma_f32_16x16x32_bf16 v[172:175], v[232:235], v[38:41], v[10:13]
	ds_read_b128 v[232:235], v247 offset:8192
	v_exp_f32_e32 v208, v180
	v_exp_f32_e32 v177, v177
	v_exp_f32_e32 v209, v181
	v_mfma_f32_16x16x32_bf16 v[168:171], v[162:165], v[38:41], v[10:13]
	ds_read_b128 v[162:165], v247 offset:10240
	v_exp_f32_e32 v178, v178
	s_nop 2
	v_exp_f32_e32 v172, v172
	v_exp_f32_e32 v210, v182
	v_mfma_f32_16x16x32_bf16 v[114:117], v[240:243], v[188:191], v[114:117]
	v_exp_f32_e32 v179, v179
	v_exp_f32_e32 v213, v168
	v_exp_f32_e32 v168, v173
	v_exp_f32_e32 v173, v169
	v_exp_f32_e32 v169, v174
	v_exp_f32_e32 v174, v170
	v_exp_f32_e32 v170, v175
	v_exp_f32_e32 v171, v171
	v_mfma_f32_16x16x32_bf16 v[98:101], v[184:187], v[188:191], v[98:101]
	v_cvt_pk_bf16_f32 v168, v172, v168
	v_cvt_pk_bf16_f32 v169, v169, v170
	v_mfma_f32_16x16x32_bf16 v[94:97], v[196:199], v[188:191], v[94:97]
	v_cvt_pk_bf16_f32 v170, v213, v173
	v_cvt_pk_bf16_f32 v171, v174, v171
	ds_read_b64 v[172:173], v248 offset:41984
	ds_read_b64 v[174:175], v248 offset:42016
	v_mfma_f32_16x16x32_bf16 v[90:93], v[200:203], v[188:191], v[90:93]
	ds_read_b64 v[212:213], v248 offset:44288
	ds_read_b64 v[214:215], v248 offset:44320
	ds_read_b128 v[200:203], v246 offset:12288
	s_waitcnt lgkmcnt(6)
	v_mfma_f32_16x16x32_bf16 v[192:195], v[232:235], v[42:45], v[6:9]
	v_exp_f32_e32 v211, v183
	v_cvt_pk_bf16_f32 v176, v176, v177
	v_cvt_pk_bf16_f32 v177, v178, v179
	s_waitcnt lgkmcnt(5)
	v_mfma_f32_16x16x32_bf16 v[196:199], v[162:165], v[42:45], v[6:9]
	v_cvt_pk_bf16_f32 v178, v208, v209
	s_nop 1
	v_exp_f32_e32 v192, v192
	v_exp_f32_e32 v193, v193
	v_mfma_f32_16x16x32_bf16 v[184:187], v[232:235], v[46:49], v[14:17]
	s_nop 1
	v_exp_f32_e32 v196, v196
	v_exp_f32_e32 v197, v197
	v_exp_f32_e32 v228, v194
	v_mfma_f32_16x16x32_bf16 v[188:191], v[162:165], v[46:49], v[14:17]
	v_exp_f32_e32 v198, v198
	s_nop 0
	v_exp_f32_e32 v184, v184
	v_exp_f32_e32 v185, v185
	v_mfma_f32_16x16x32_bf16 v[86:89], v[240:243], v[168:171], v[86:89]
	v_exp_f32_e32 v186, v186
	s_nop 1
	v_exp_f32_e32 v188, v188
	v_exp_f32_e32 v189, v189
	s_waitcnt lgkmcnt(3)
	v_mfma_f32_16x16x32_bf16 v[78:81], v[172:175], v[168:171], v[78:81]
	v_exp_f32_e32 v190, v190
	v_exp_f32_e32 v187, v187
	v_exp_f32_e32 v191, v191
	s_waitcnt lgkmcnt(1)
	v_mfma_f32_16x16x32_bf16 v[74:77], v[212:215], v[168:171], v[74:77]
	v_cvt_pk_bf16_f32 v179, v210, v211
	v_cvt_pk_bf16_f32 v184, v184, v185
	v_cvt_pk_bf16_f32 v185, v186, v187
	v_mfma_f32_16x16x32_bf16 v[70:73], v[216:219], v[168:171], v[70:73]
	v_cvt_pk_bf16_f32 v186, v188, v189
	v_cvt_pk_bf16_f32 v187, v190, v191
	v_mfma_f32_16x16x32_bf16 v[62:65], v[220:223], v[168:171], v[62:65]
	v_exp_f32_e32 v169, v195
	v_exp_f32_e32 v171, v199
	v_cvt_pk_bf16_f32 v168, v192, v193
	s_waitcnt lgkmcnt(0)
	v_mfma_f32_16x16x32_bf16 v[180:183], v[200:203], v[34:37], v[2:5]
	v_cvt_pk_bf16_f32 v169, v228, v169
	ds_read_b128 v[162:165], v247 offset:14336
	v_cvt_pk_bf16_f32 v170, v196, v197
	v_cvt_pk_bf16_f32 v171, v198, v171
	v_mfma_f32_16x16x32_bf16 v[208:211], v[204:207], v[34:37], v[2:5]
	v_mfma_f32_16x16x32_bf16 v[200:203], v[200:203], v[38:41], v[10:13]
	s_nop 2
	v_exp_f32_e32 v180, v180
	s_nop 2
	v_exp_f32_e32 v188, v208
	v_mfma_f32_16x16x32_bf16 v[204:207], v[204:207], v[38:41], v[10:13]
	v_mfma_f32_16x16x32_bf16 v[122:125], v[172:175], v[176:179], v[122:125]
	v_exp_f32_e32 v190, v202
	s_nop 5
	v_exp_f32_e32 v189, v205
	v_exp_f32_e32 v191, v207
	v_mfma_f32_16x16x32_bf16 v[102:105], v[172:175], v[168:171], v[102:105]
	v_mfma_f32_16x16x32_bf16 v[58:61], v[172:175], v[184:187], v[58:61]
	v_exp_f32_e32 v172, v181
	v_exp_f32_e32 v174, v209
	v_exp_f32_e32 v173, v182
	v_exp_f32_e32 v181, v183
	v_mfma_f32_16x16x32_bf16 v[126:129], v[240:243], v[176:179], v[126:129]
	v_exp_f32_e32 v175, v210
	v_exp_f32_e32 v182, v211
	v_cvt_pk_bf16_f32 v172, v180, v172
	v_mfma_f32_16x16x32_bf16 v[118:121], v[212:215], v[176:179], v[118:121]
	v_cvt_pk_bf16_f32 v173, v173, v181
	v_cvt_pk_bf16_f32 v174, v188, v174
	v_exp_f32_e32 v180, v200
	v_mfma_f32_16x16x32_bf16 v[110:113], v[216:219], v[176:179], v[110:113]
	v_exp_f32_e32 v188, v204
	v_exp_f32_e32 v181, v201
	v_cvt_pk_bf16_f32 v175, v175, v182
	v_mfma_f32_16x16x32_bf16 v[106:109], v[220:223], v[176:179], v[106:109]
	v_mfma_f32_16x16x32_bf16 v[114:117], v[240:243], v[168:171], v[114:117]
	v_mfma_f32_16x16x32_bf16 v[98:101], v[212:215], v[168:171], v[98:101]
	v_mfma_f32_16x16x32_bf16 v[94:97], v[216:219], v[168:171], v[94:97]
	v_mfma_f32_16x16x32_bf16 v[90:93], v[220:223], v[168:171], v[90:93]
	v_exp_f32_e32 v171, v206
	v_exp_f32_e32 v169, v203
	v_mfma_f32_16x16x32_bf16 v[82:85], v[240:243], v[184:187], v[82:85]
	v_cvt_pk_bf16_f32 v168, v180, v181
	ds_read_b64 v[180:181], v248 offset:42048
	ds_read_b64 v[182:183], v248 offset:42080
	v_cvt_pk_bf16_f32 v170, v188, v189
	v_mfma_f32_16x16x32_bf16 v[54:57], v[212:215], v[184:187], v[54:57]
	v_cvt_pk_bf16_f32 v169, v190, v169
	v_cvt_pk_bf16_f32 v171, v171, v191
	v_mfma_f32_16x16x32_bf16 v[50:53], v[216:219], v[184:187], v[50:53]
	ds_read_b64 v[188:189], v248 offset:46656
	ds_read_b64 v[190:191], v248 offset:46688
	ds_read_b64 v[200:201], v248 offset:48960
	ds_read_b64 v[202:203], v248 offset:48992
	v_mfma_f32_16x16x32_bf16 v[66:69], v[220:223], v[184:187], v[66:69]
	ds_read_b64 v[184:185], v248 offset:44352
	ds_read_b64 v[186:187], v248 offset:44384
	v_mfma_f32_16x16x32_bf16 v[192:195], v[224:227], v[42:45], v[6:9]
	s_waitcnt lgkmcnt(8)
	v_mfma_f32_16x16x32_bf16 v[196:199], v[162:165], v[42:45], v[6:9]
	v_mfma_f32_16x16x32_bf16 v[224:227], v[224:227], v[46:49], v[14:17]
	s_nop 4
	v_exp_f32_e32 v192, v192
	s_nop 0
	v_exp_f32_e32 v196, v196
	v_exp_f32_e32 v193, v193
	v_mfma_f32_16x16x32_bf16 v[176:179], v[162:165], v[46:49], v[14:17]
	v_exp_f32_e32 v197, v197
	v_exp_f32_e32 v194, v194
	v_exp_f32_e32 v195, v195
	v_mfma_f32_16x16x32_bf16 v[126:129], v[240:243], v[172:175], v[126:129]
	v_exp_f32_e32 v198, v198
	v_exp_f32_e32 v199, v199
	v_cvt_pk_bf16_f32 v192, v192, v193
	v_mfma_f32_16x16x32_bf16 v[86:89], v[240:243], v[168:171], v[86:89]
	v_cvt_pk_bf16_f32 v193, v194, v195
	v_cvt_pk_bf16_f32 v194, v196, v197
	v_exp_f32_e32 v196, v224
	s_waitcnt lgkmcnt(6)
	v_mfma_f32_16x16x32_bf16 v[122:125], v[180:183], v[172:175], v[122:125]
	v_exp_f32_e32 v176, v176
	v_exp_f32_e32 v197, v225
	v_cvt_pk_bf16_f32 v195, v198, v199
	v_mfma_f32_16x16x32_bf16 v[78:81], v[180:183], v[168:171], v[78:81]
	s_waitcnt lgkmcnt(0)
	v_mfma_f32_16x16x32_bf16 v[118:121], v[184:187], v[172:175], v[118:121]
	v_mfma_f32_16x16x32_bf16 v[74:77], v[184:187], v[168:171], v[74:77]
	v_mfma_f32_16x16x32_bf16 v[110:113], v[188:191], v[172:175], v[110:113]
	v_mfma_f32_16x16x32_bf16 v[70:73], v[188:191], v[168:171], v[70:73]
	v_mfma_f32_16x16x32_bf16 v[106:109], v[200:203], v[172:175], v[106:109]
	v_exp_f32_e32 v172, v177
	v_exp_f32_e32 v173, v226
	v_exp_f32_e32 v174, v178
	v_mfma_f32_16x16x32_bf16 v[62:65], v[200:203], v[168:171], v[62:65]
	v_exp_f32_e32 v169, v227
	v_exp_f32_e32 v171, v179
	v_cvt_pk_bf16_f32 v168, v196, v197
	v_cvt_pk_bf16_f32 v170, v176, v172
	v_cvt_pk_bf16_f32 v169, v173, v169
	v_cvt_pk_bf16_f32 v171, v174, v171
	v_mfma_f32_16x16x32_bf16 v[114:117], v[240:243], v[192:195], v[114:117]
	s_nop 0
	v_mfma_f32_16x16x32_bf16 v[82:85], v[240:243], v[168:171], v[82:85]
	v_mfma_f32_16x16x32_bf16 v[102:105], v[180:183], v[192:195], v[102:105]
	v_mfma_f32_16x16x32_bf16 v[58:61], v[180:183], v[168:171], v[58:61]
	v_mfma_f32_16x16x32_bf16 v[98:101], v[184:187], v[192:195], v[98:101]
	v_mfma_f32_16x16x32_bf16 v[54:57], v[184:187], v[168:171], v[54:57]
	v_mfma_f32_16x16x32_bf16 v[94:97], v[188:191], v[192:195], v[94:97]
	v_mfma_f32_16x16x32_bf16 v[50:53], v[188:191], v[168:171], v[50:53]
	v_mfma_f32_16x16x32_bf16 v[90:93], v[200:203], v[192:195], v[90:93]
	v_mfma_f32_16x16x32_bf16 v[66:69], v[200:203], v[168:171], v[66:69]
	v_xor_b32_e32 v246, 0x4000, v246
	v_xor_b32_e32 v247, 0x4000, v247
	v_xor_b32_e32 v244, 0x4000, v244
	v_add_u32_e32 v248, s99, v248
	v_add_u32_e32 v245, s99, v245
	s_sub_i32 s99, 0, s99
	s_cbranch_vccnz .LBB0_928
.LBB0_926:
	s_and_b32 s0, s12, 0x80
	s_lshl_b32 s1, s0, 7
	s_add_i32 s39, s1, 0
	s_lshl_b32 s0, s0, 4
	s_add_i32 s2, s39, s0
	s_cmpk_gt_u32 s38, 0x101
	s_cselect_b64 s[0:1], -1, 0
	s_and_b64 vcc, exec, s[0:1]
	s_waitcnt vmcnt(3)
	ds_write_b128 v244, v[18:21]
	s_waitcnt vmcnt(1)
	ds_write_b128 v245, v[22:25] offset:32768
	s_waitcnt vmcnt(1)
	ds_write_b128 v244, v[26:29] offset:8192
	s_waitcnt vmcnt(0)
	ds_write_b128 v245, v[30:33] offset:41984
	s_waitcnt lgkmcnt(0)
	s_barrier
	ds_read_b128 v[130:133], v246
	ds_read_b128 v[168:171], v246 offset:2048
	ds_read_b128 v[162:165], v247
	ds_read_b128 v[232:235], v246 offset:4096
	s_cbranch_vccnz .LBB0_925
	s_cmp_eq_u32 s12, 0
	s_cbranch_scc0 .Lpf_next_925
	v_add_u32_e32 v250, s36, v161
	v_mad_i64_i32 v[250:251], s[40:41], v250, s21, v[146:147]
	v_add_u32_e32 v252, s37, v161
	v_mad_i64_i32 v[252:253], s[40:41], v252, s21, v[146:147]
	s_sub_i32 s100, s35, s36
	s_mul_hi_i32 s101, s100, 0x1640
	s_mul_i32 s100, s100, 0x1640
	s_branch .Lpf_load_925

.LBB0_2159:
	s_waitcnt lgkmcnt(3)
	v_mfma_f32_16x16x32_bf16 v[170:173], v[130:133], v[34:37], v[2:5]
	ds_read_b128 v[182:185], v247 offset:2048
	v_mfma_f32_16x16x32_bf16 v[178:181], v[130:133], v[38:41], v[10:13]
	s_nop 2
	s_nop 1
	s_nop 0
	v_exp_f32_e32 v198, v170
	v_exp_f32_e32 v199, v173
	s_waitcnt lgkmcnt(3)
	v_mfma_f32_16x16x32_bf16 v[174:177], v[166:169], v[34:37], v[2:5]
	v_exp_f32_e32 v178, v178
	ds_read_b64 v[214:215], v248 offset:37376
	ds_read_b64 v[216:217], v248 offset:37408
	v_mfma_f32_16x16x32_bf16 v[166:169], v[166:169], v[38:41], v[10:13]
	ds_read_b64 v[218:219], v248 offset:39680
	ds_read_b64 v[220:221], v248 offset:39712
	s_nop 2
	v_exp_f32_e32 v202, v174
	v_exp_f32_e32 v174, v171
	s_waitcnt lgkmcnt(6)
	v_mfma_f32_16x16x32_bf16 v[186:189], v[160:163], v[42:45], v[6:9]
	v_exp_f32_e32 v203, v175
	v_exp_f32_e32 v211, v166
	v_exp_f32_e32 v166, v179
	v_mfma_f32_16x16x32_bf16 v[194:197], v[160:163], v[46:49], v[14:17]
	v_exp_f32_e32 v179, v167
	v_exp_f32_e32 v167, v180
	v_exp_f32_e32 v180, v168
	v_exp_f32_e32 v168, v181
	v_exp_f32_e32 v169, v169
	v_exp_f32_e32 v175, v172
	v_cvt_pk_bf16_f32 v166, v178, v166
	v_cvt_pk_bf16_f32 v167, v167, v168
	v_cvt_pk_bf16_f32 v168, v211, v179
	v_cvt_pk_bf16_f32 v169, v180, v169
	ds_read_b64 v[178:179], v248 offset:32768
	ds_read_b64 v[180:181], v248 offset:32800
	ds_read_b64 v[210:211], v248 offset:35072
	ds_read_b64 v[212:213], v248 offset:35104
	ds_read_b128 v[170:173], v246 offset:6144
	v_cvt_pk_bf16_f32 v174, v198, v174
	v_cvt_pk_bf16_f32 v175, v175, v199
	s_waitcnt lgkmcnt(10)
	v_mfma_f32_16x16x32_bf16 v[198:201], v[230:233], v[34:37], v[2:5]
	v_exp_f32_e32 v229, v188
	v_exp_f32_e32 v204, v176
	v_exp_f32_e32 v177, v177
	v_mfma_f32_16x16x32_bf16 v[206:209], v[230:233], v[38:41], v[10:13]
	v_exp_f32_e32 v186, v186
	s_waitcnt lgkmcnt(9)
	v_mfma_f32_16x16x32_bf16 v[190:193], v[182:185], v[42:45], v[6:9]
	v_exp_f32_e32 v187, v187
	v_exp_f32_e32 v194, v194
	v_cvt_pk_bf16_f32 v176, v202, v203
	v_mfma_f32_16x16x32_bf16 v[182:185], v[182:185], v[46:49], v[14:17]
	v_cvt_pk_bf16_f32 v177, v204, v177
	s_nop 2
	v_exp_f32_e32 v190, v190
	v_exp_f32_e32 v191, v191
	v_mfma_f32_16x16x32_bf16 v[86:89], v[240:243], v[166:169], v[86:89]
	v_exp_f32_e32 v192, v192
	v_exp_f32_e32 v185, v185
	ds_read_b128 v[222:225], v247 offset:4096
	s_waitcnt lgkmcnt(4)
	v_mfma_f32_16x16x32_bf16 v[78:81], v[178:181], v[166:169], v[78:81]
	s_add_i32 s36, s36, 2
	s_addk_i32 s10, 0x80
	v_lshl_add_u64 v[146:147], v[146:147], 0, s[14:15]
	s_waitcnt lgkmcnt(2)
	v_mfma_f32_16x16x32_bf16 v[74:77], v[210:213], v[166:169], v[74:77]
	s_and_b64 vcc, exec, s[0:1]
	v_mfma_f32_16x16x32_bf16 v[70:73], v[214:217], v[166:169], v[70:73]
	v_mfma_f32_16x16x32_bf16 v[62:65], v[218:221], v[166:169], v[62:65]
	v_exp_f32_e32 v167, v189
	v_exp_f32_e32 v169, v193
	v_cvt_pk_bf16_f32 v166, v186, v187
	s_waitcnt lgkmcnt(1)
	v_mfma_f32_16x16x32_bf16 v[202:205], v[170:173], v[34:37], v[2:5]
	v_cvt_pk_bf16_f32 v167, v229, v167
	v_exp_f32_e32 v229, v182
	v_exp_f32_e32 v182, v195
	v_exp_f32_e32 v195, v183
	v_exp_f32_e32 v183, v196
	v_exp_f32_e32 v196, v184
	v_exp_f32_e32 v184, v197
	ds_read_b128 v[160:163], v247 offset:6144
	v_cvt_pk_bf16_f32 v168, v190, v191
	v_cvt_pk_bf16_f32 v169, v192, v169
	v_cvt_pk_bf16_f32 v182, v194, v182
	v_cvt_pk_bf16_f32 v183, v183, v184
	v_cvt_pk_bf16_f32 v184, v229, v195
	v_cvt_pk_bf16_f32 v185, v196, v185
	v_mfma_f32_16x16x32_bf16 v[170:173], v[170:173], v[38:41], v[10:13]
	v_exp_f32_e32 v194, v198
	v_exp_f32_e32 v195, v202
	v_exp_f32_e32 v196, v199
	v_mfma_f32_16x16x32_bf16 v[122:125], v[178:181], v[174:177], v[122:125]
	v_exp_f32_e32 v198, v205
	v_exp_f32_e32 v197, v201
	v_mfma_f32_16x16x32_bf16 v[102:105], v[178:181], v[166:169], v[102:105]
	v_mfma_f32_16x16x32_bf16 v[58:61], v[178:181], v[182:185], v[58:61]
	v_exp_f32_e32 v180, v203
	v_exp_f32_e32 v181, v204
	v_exp_f32_e32 v179, v200
	v_mfma_f32_16x16x32_bf16 v[126:129], v[240:243], v[174:177], v[126:129]
	v_cvt_pk_bf16_f32 v178, v194, v196
	v_cvt_pk_bf16_f32 v180, v195, v180
	v_cvt_pk_bf16_f32 v181, v181, v198
	v_mfma_f32_16x16x32_bf16 v[118:121], v[210:213], v[174:177], v[118:121]
	v_exp_f32_e32 v194, v206
	v_exp_f32_e32 v195, v170
	v_exp_f32_e32 v170, v207
	v_mfma_f32_16x16x32_bf16 v[110:113], v[214:217], v[174:177], v[110:113]
	v_exp_f32_e32 v198, v172
	v_cvt_pk_bf16_f32 v179, v179, v197
	v_exp_f32_e32 v196, v171
	v_mfma_f32_16x16x32_bf16 v[106:109], v[218:221], v[174:177], v[106:109]
	v_exp_f32_e32 v197, v208
	ds_read_b128 v[202:205], v246 offset:14336
	v_mfma_f32_16x16x32_bf16 v[114:117], v[240:243], v[166:169], v[114:117]
	v_mfma_f32_16x16x32_bf16 v[98:101], v[210:213], v[166:169], v[98:101]
	v_mfma_f32_16x16x32_bf16 v[94:97], v[214:217], v[166:169], v[94:97]
	v_mfma_f32_16x16x32_bf16 v[90:93], v[218:221], v[166:169], v[90:93]
	v_exp_f32_e32 v169, v173
	v_exp_f32_e32 v167, v209
	v_cvt_pk_bf16_f32 v166, v194, v170
	v_mfma_f32_16x16x32_bf16 v[82:85], v[240:243], v[182:185], v[82:85]
	v_cvt_pk_bf16_f32 v169, v198, v169
	v_mfma_f32_16x16x32_bf16 v[54:57], v[210:213], v[182:185], v[54:57]
	ds_read_b64 v[170:171], v248 offset:32832
	ds_read_b64 v[172:173], v248 offset:32864
	v_cvt_pk_bf16_f32 v167, v197, v167
	v_mfma_f32_16x16x32_bf16 v[50:53], v[214:217], v[182:185], v[50:53]
	v_cvt_pk_bf16_f32 v168, v195, v196
	ds_read_b64 v[194:195], v248 offset:37440
	ds_read_b64 v[196:197], v248 offset:37472
	ds_read_b64 v[198:199], v248 offset:39744
	ds_read_b64 v[200:201], v248 offset:39776
	v_mfma_f32_16x16x32_bf16 v[66:69], v[218:221], v[182:185], v[66:69]
	ds_read_b128 v[230:233], v246 offset:8192
	ds_read_b64 v[182:183], v248 offset:35136
	ds_read_b64 v[184:185], v248 offset:35168
	ds_read_b128 v[234:237], v246 offset:10240
	s_waitcnt lgkmcnt(12)
	v_mfma_f32_16x16x32_bf16 v[186:189], v[222:225], v[42:45], v[6:9]
	ds_read_b64 v[214:215], v248 offset:46592
	ds_read_b64 v[216:217], v248 offset:46624
	s_waitcnt lgkmcnt(13)
	v_mfma_f32_16x16x32_bf16 v[190:193], v[160:163], v[42:45], v[6:9]
	ds_read_b64 v[218:219], v248 offset:48896
	ds_read_b64 v[220:221], v248 offset:48928
	s_nop 1
	v_exp_f32_e32 v186, v186
	v_exp_f32_e32 v187, v187
	v_mfma_f32_16x16x32_bf16 v[222:225], v[222:225], v[46:49], v[14:17]
	v_exp_f32_e32 v188, v188
	s_nop 0
	v_exp_f32_e32 v190, v190
	v_exp_f32_e32 v191, v191
	v_mfma_f32_16x16x32_bf16 v[174:177], v[160:163], v[46:49], v[14:17]
	v_exp_f32_e32 v189, v189
	v_exp_f32_e32 v192, v192
	v_exp_f32_e32 v193, v193
	v_mfma_f32_16x16x32_bf16 v[126:129], v[240:243], v[178:181], v[126:129]
	v_cvt_pk_bf16_f32 v186, v186, v187
	v_cvt_pk_bf16_f32 v187, v188, v189
	v_cvt_pk_bf16_f32 v188, v190, v191
	v_mfma_f32_16x16x32_bf16 v[86:89], v[240:243], v[166:169], v[86:89]
	v_exp_f32_e32 v190, v222
	v_exp_f32_e32 v174, v174
	v_exp_f32_e32 v191, v223
	s_waitcnt lgkmcnt(12)
	v_mfma_f32_16x16x32_bf16 v[122:125], v[170:173], v[178:181], v[122:125]
	v_exp_f32_e32 v175, v175
	v_exp_f32_e32 v176, v176
	v_cvt_pk_bf16_f32 v189, v192, v193
	v_mfma_f32_16x16x32_bf16 v[78:81], v[170:173], v[166:169], v[78:81]
	s_waitcnt lgkmcnt(5)
	v_mfma_f32_16x16x32_bf16 v[118:121], v[182:185], v[178:181], v[118:121]
	v_mfma_f32_16x16x32_bf16 v[74:77], v[182:185], v[166:169], v[74:77]
	ds_read_b128 v[160:163], v247 offset:8192
	v_mfma_f32_16x16x32_bf16 v[110:113], v[194:197], v[178:181], v[110:113]
	v_mfma_f32_16x16x32_bf16 v[70:73], v[194:197], v[166:169], v[70:73]
	v_mfma_f32_16x16x32_bf16 v[106:109], v[198:201], v[178:181], v[106:109]
	v_exp_f32_e32 v178, v224
	v_mfma_f32_16x16x32_bf16 v[62:65], v[198:201], v[166:169], v[62:65]
	v_exp_f32_e32 v167, v225
	v_exp_f32_e32 v169, v177
	v_cvt_pk_bf16_f32 v166, v190, v191
	v_cvt_pk_bf16_f32 v168, v174, v175
	v_cvt_pk_bf16_f32 v167, v178, v167
	v_cvt_pk_bf16_f32 v169, v176, v169
	v_mfma_f32_16x16x32_bf16 v[102:105], v[170:173], v[186:189], v[102:105]
	ds_read_b128 v[222:225], v247 offset:12288
	v_mfma_f32_16x16x32_bf16 v[82:85], v[240:243], v[166:169], v[82:85]
	v_mfma_f32_16x16x32_bf16 v[58:61], v[170:173], v[166:169], v[58:61]
	v_mfma_f32_16x16x32_bf16 v[54:57], v[182:185], v[166:169], v[54:57]
	v_mfma_f32_16x16x32_bf16 v[50:53], v[194:197], v[166:169], v[50:53]
	v_mfma_f32_16x16x32_bf16 v[66:69], v[198:201], v[166:169], v[66:69]
	v_mfma_f32_16x16x32_bf16 v[174:177], v[230:233], v[34:37], v[2:5]
	s_waitcnt lgkmcnt(6)
	v_mfma_f32_16x16x32_bf16 v[178:181], v[234:237], v[34:37], v[2:5]
	s_nop 5
	v_exp_f32_e32 v174, v174
	v_mfma_f32_16x16x32_bf16 v[170:173], v[230:233], v[38:41], v[10:13]
	ds_read_b128 v[230:233], v247 offset:10240
	v_exp_f32_e32 v206, v178
	v_exp_f32_e32 v175, v175
	v_exp_f32_e32 v207, v179
	v_mfma_f32_16x16x32_bf16 v[166:169], v[234:237], v[38:41], v[10:13]
	v_exp_f32_e32 v176, v176
	s_nop 2
	v_exp_f32_e32 v170, v170
	v_exp_f32_e32 v208, v180
	v_mfma_f32_16x16x32_bf16 v[114:117], v[240:243], v[186:189], v[114:117]
	v_exp_f32_e32 v177, v177
	v_exp_f32_e32 v211, v166
	v_exp_f32_e32 v166, v171
	v_exp_f32_e32 v171, v167
	v_exp_f32_e32 v167, v172
	v_exp_f32_e32 v172, v168
	v_exp_f32_e32 v168, v173
	v_exp_f32_e32 v169, v169
	v_mfma_f32_16x16x32_bf16 v[98:101], v[182:185], v[186:189], v[98:101]
	v_cvt_pk_bf16_f32 v166, v170, v166
	v_cvt_pk_bf16_f32 v167, v167, v168
	v_mfma_f32_16x16x32_bf16 v[94:97], v[194:197], v[186:189], v[94:97]
	v_cvt_pk_bf16_f32 v168, v211, v171
	v_cvt_pk_bf16_f32 v169, v172, v169
	ds_read_b64 v[170:171], v248 offset:41984
	ds_read_b64 v[172:173], v248 offset:42016
	v_mfma_f32_16x16x32_bf16 v[90:93], v[198:201], v[186:189], v[90:93]
	ds_read_b64 v[210:211], v248 offset:44288
	ds_read_b64 v[212:213], v248 offset:44320
	ds_read_b128 v[198:201], v246 offset:12288
	s_waitcnt lgkmcnt(7)
	v_mfma_f32_16x16x32_bf16 v[190:193], v[160:163], v[42:45], v[6:9]
	v_exp_f32_e32 v209, v181
	v_cvt_pk_bf16_f32 v174, v174, v175
	v_cvt_pk_bf16_f32 v175, v176, v177
	s_waitcnt lgkmcnt(5)
	v_mfma_f32_16x16x32_bf16 v[194:197], v[230:233], v[42:45], v[6:9]
	v_cvt_pk_bf16_f32 v176, v206, v207
	s_nop 1
	v_exp_f32_e32 v190, v190
	v_exp_f32_e32 v191, v191
	v_mfma_f32_16x16x32_bf16 v[182:185], v[160:163], v[46:49], v[14:17]
	s_nop 1
	v_exp_f32_e32 v194, v194
	v_exp_f32_e32 v195, v195
	v_exp_f32_e32 v226, v192
	v_mfma_f32_16x16x32_bf16 v[186:189], v[230:233], v[46:49], v[14:17]
	v_exp_f32_e32 v196, v196
	s_nop 0
	v_exp_f32_e32 v182, v182
	v_exp_f32_e32 v183, v183
	v_mfma_f32_16x16x32_bf16 v[86:89], v[240:243], v[166:169], v[86:89]
	v_exp_f32_e32 v184, v184
	s_nop 1
	v_exp_f32_e32 v186, v186
	v_exp_f32_e32 v187, v187
	s_waitcnt lgkmcnt(3)
	v_mfma_f32_16x16x32_bf16 v[78:81], v[170:173], v[166:169], v[78:81]
	v_exp_f32_e32 v188, v188
	v_exp_f32_e32 v185, v185
	v_exp_f32_e32 v189, v189
	s_waitcnt lgkmcnt(1)
	v_mfma_f32_16x16x32_bf16 v[74:77], v[210:213], v[166:169], v[74:77]
	v_cvt_pk_bf16_f32 v177, v208, v209
	v_cvt_pk_bf16_f32 v182, v182, v183
	v_cvt_pk_bf16_f32 v183, v184, v185
	v_mfma_f32_16x16x32_bf16 v[70:73], v[214:217], v[166:169], v[70:73]
	v_cvt_pk_bf16_f32 v184, v186, v187
	v_cvt_pk_bf16_f32 v185, v188, v189
	v_mfma_f32_16x16x32_bf16 v[62:65], v[218:221], v[166:169], v[62:65]
	v_exp_f32_e32 v167, v193
	v_exp_f32_e32 v169, v197
	v_cvt_pk_bf16_f32 v166, v190, v191
	s_waitcnt lgkmcnt(0)
	v_mfma_f32_16x16x32_bf16 v[178:181], v[198:201], v[34:37], v[2:5]
	v_cvt_pk_bf16_f32 v167, v226, v167
	ds_read_b128 v[160:163], v247 offset:14336
	v_cvt_pk_bf16_f32 v168, v194, v195
	v_cvt_pk_bf16_f32 v169, v196, v169
	v_mfma_f32_16x16x32_bf16 v[206:209], v[202:205], v[34:37], v[2:5]
	v_mfma_f32_16x16x32_bf16 v[198:201], v[198:201], v[38:41], v[10:13]
	s_nop 2
	v_exp_f32_e32 v178, v178
	s_nop 2
	v_exp_f32_e32 v186, v206
	v_mfma_f32_16x16x32_bf16 v[202:205], v[202:205], v[38:41], v[10:13]
	v_mfma_f32_16x16x32_bf16 v[122:125], v[170:173], v[174:177], v[122:125]
	v_exp_f32_e32 v188, v200
	s_nop 5
	v_exp_f32_e32 v187, v203
	v_exp_f32_e32 v189, v205
	v_mfma_f32_16x16x32_bf16 v[102:105], v[170:173], v[166:169], v[102:105]
	v_mfma_f32_16x16x32_bf16 v[58:61], v[170:173], v[182:185], v[58:61]
	v_exp_f32_e32 v170, v179
	v_exp_f32_e32 v172, v207
	v_exp_f32_e32 v171, v180
	v_exp_f32_e32 v179, v181
	v_mfma_f32_16x16x32_bf16 v[126:129], v[240:243], v[174:177], v[126:129]
	v_exp_f32_e32 v173, v208
	v_exp_f32_e32 v180, v209
	v_cvt_pk_bf16_f32 v170, v178, v170
	v_mfma_f32_16x16x32_bf16 v[118:121], v[210:213], v[174:177], v[118:121]
	v_cvt_pk_bf16_f32 v171, v171, v179
	v_cvt_pk_bf16_f32 v172, v186, v172
	v_exp_f32_e32 v178, v198
	v_mfma_f32_16x16x32_bf16 v[110:113], v[214:217], v[174:177], v[110:113]
	v_exp_f32_e32 v186, v202
	v_exp_f32_e32 v179, v199
	v_cvt_pk_bf16_f32 v173, v173, v180
	v_mfma_f32_16x16x32_bf16 v[106:109], v[218:221], v[174:177], v[106:109]
	v_mfma_f32_16x16x32_bf16 v[114:117], v[240:243], v[166:169], v[114:117]
	v_mfma_f32_16x16x32_bf16 v[98:101], v[210:213], v[166:169], v[98:101]
	v_mfma_f32_16x16x32_bf16 v[94:97], v[214:217], v[166:169], v[94:97]
	v_mfma_f32_16x16x32_bf16 v[90:93], v[218:221], v[166:169], v[90:93]
	v_exp_f32_e32 v169, v204
	v_exp_f32_e32 v167, v201
	v_mfma_f32_16x16x32_bf16 v[82:85], v[240:243], v[182:185], v[82:85]
	v_cvt_pk_bf16_f32 v166, v178, v179
	ds_read_b64 v[178:179], v248 offset:42048
	ds_read_b64 v[180:181], v248 offset:42080
	v_cvt_pk_bf16_f32 v168, v186, v187
	v_mfma_f32_16x16x32_bf16 v[54:57], v[210:213], v[182:185], v[54:57]
	v_cvt_pk_bf16_f32 v167, v188, v167
	v_cvt_pk_bf16_f32 v169, v169, v189
	v_mfma_f32_16x16x32_bf16 v[50:53], v[214:217], v[182:185], v[50:53]
	ds_read_b64 v[186:187], v248 offset:46656
	ds_read_b64 v[188:189], v248 offset:46688
	ds_read_b64 v[198:199], v248 offset:48960
	ds_read_b64 v[200:201], v248 offset:48992
	v_mfma_f32_16x16x32_bf16 v[66:69], v[218:221], v[182:185], v[66:69]
	ds_read_b64 v[182:183], v248 offset:44352
	ds_read_b64 v[184:185], v248 offset:44384
	v_mfma_f32_16x16x32_bf16 v[190:193], v[222:225], v[42:45], v[6:9]
	s_waitcnt lgkmcnt(8)
	v_mfma_f32_16x16x32_bf16 v[194:197], v[160:163], v[42:45], v[6:9]
	v_mfma_f32_16x16x32_bf16 v[222:225], v[222:225], v[46:49], v[14:17]
	s_nop 4
	v_exp_f32_e32 v190, v190
	s_nop 0
	v_exp_f32_e32 v194, v194
	v_exp_f32_e32 v191, v191
	v_mfma_f32_16x16x32_bf16 v[174:177], v[160:163], v[46:49], v[14:17]
	v_exp_f32_e32 v195, v195
	v_exp_f32_e32 v192, v192
	v_exp_f32_e32 v193, v193
	v_mfma_f32_16x16x32_bf16 v[126:129], v[240:243], v[170:173], v[126:129]
	v_exp_f32_e32 v196, v196
	v_exp_f32_e32 v197, v197
	v_cvt_pk_bf16_f32 v190, v190, v191
	v_mfma_f32_16x16x32_bf16 v[86:89], v[240:243], v[166:169], v[86:89]
	v_cvt_pk_bf16_f32 v191, v192, v193
	v_cvt_pk_bf16_f32 v192, v194, v195
	v_exp_f32_e32 v194, v222
	s_waitcnt lgkmcnt(6)
	v_mfma_f32_16x16x32_bf16 v[122:125], v[178:181], v[170:173], v[122:125]
	v_exp_f32_e32 v174, v174
	v_exp_f32_e32 v195, v223
	v_cvt_pk_bf16_f32 v193, v196, v197
	v_mfma_f32_16x16x32_bf16 v[78:81], v[178:181], v[166:169], v[78:81]
	s_waitcnt lgkmcnt(0)
	v_mfma_f32_16x16x32_bf16 v[118:121], v[182:185], v[170:173], v[118:121]
	v_mfma_f32_16x16x32_bf16 v[74:77], v[182:185], v[166:169], v[74:77]
	v_mfma_f32_16x16x32_bf16 v[110:113], v[186:189], v[170:173], v[110:113]
	v_mfma_f32_16x16x32_bf16 v[70:73], v[186:189], v[166:169], v[70:73]
	v_mfma_f32_16x16x32_bf16 v[106:109], v[198:201], v[170:173], v[106:109]
	v_exp_f32_e32 v170, v175
	v_exp_f32_e32 v171, v224
	v_exp_f32_e32 v172, v176
	v_mfma_f32_16x16x32_bf16 v[62:65], v[198:201], v[166:169], v[62:65]
	v_exp_f32_e32 v167, v225
	v_exp_f32_e32 v169, v177
	v_cvt_pk_bf16_f32 v166, v194, v195
	v_cvt_pk_bf16_f32 v168, v174, v170
	v_cvt_pk_bf16_f32 v167, v171, v167
	v_cvt_pk_bf16_f32 v169, v172, v169
	v_mfma_f32_16x16x32_bf16 v[114:117], v[240:243], v[190:193], v[114:117]
	s_nop 0
	v_mfma_f32_16x16x32_bf16 v[82:85], v[240:243], v[166:169], v[82:85]
	v_mfma_f32_16x16x32_bf16 v[102:105], v[178:181], v[190:193], v[102:105]
	v_mfma_f32_16x16x32_bf16 v[58:61], v[178:181], v[166:169], v[58:61]
	v_mfma_f32_16x16x32_bf16 v[98:101], v[182:185], v[190:193], v[98:101]
	v_mfma_f32_16x16x32_bf16 v[54:57], v[182:185], v[166:169], v[54:57]
	v_mfma_f32_16x16x32_bf16 v[94:97], v[186:189], v[190:193], v[94:97]
	v_mfma_f32_16x16x32_bf16 v[50:53], v[186:189], v[166:169], v[50:53]
	v_mfma_f32_16x16x32_bf16 v[90:93], v[198:201], v[190:193], v[90:93]
	v_mfma_f32_16x16x32_bf16 v[66:69], v[198:201], v[166:169], v[66:69]
	v_xor_b32_e32 v246, 0x4000, v246
	v_xor_b32_e32 v247, 0x4000, v247
	v_xor_b32_e32 v244, 0x4000, v244
	v_add_u32_e32 v248, s99, v248
	v_add_u32_e32 v245, s99, v245
	s_sub_i32 s99, 0, s99
	s_cbranch_vccnz .LBB0_2162
.LBB0_2160:
	s_and_b32 s0, s10, 0x80
	s_lshl_b32 s1, s0, 7
	s_add_i32 s37, s1, 0
	s_lshl_b32 s0, s0, 4
	s_add_i32 s2, s37, s0
	s_cmpk_gt_u32 s36, 0x101
	s_cselect_b64 s[0:1], -1, 0
	s_and_b64 vcc, exec, s[0:1]
	s_waitcnt vmcnt(3)
	ds_write_b128 v244, v[18:21]
	s_waitcnt vmcnt(1)
	ds_write_b128 v245, v[22:25] offset:32768
	s_waitcnt vmcnt(1)
	ds_write_b128 v244, v[26:29] offset:8192
	s_waitcnt vmcnt(0)
	ds_write_b128 v245, v[30:33] offset:41984
	s_waitcnt lgkmcnt(0)
	s_barrier
	ds_read_b128 v[130:133], v246
	ds_read_b128 v[166:169], v246 offset:2048
	ds_read_b128 v[160:163], v247
	ds_read_b128 v[230:233], v246 offset:4096
	s_cbranch_vccnz .LBB0_2159
	s_cmp_eq_u32 s10, 0
	s_cbranch_scc0 .Lpf_next_2159
	v_add_u32_e32 v250, s34, v159
	v_mad_i64_i32 v[250:251], s[38:39], v250, s19, v[144:145]
	v_add_u32_e32 v252, s35, v159
	v_mad_i64_i32 v[252:253], s[38:39], v252, s19, v[144:145]
	s_sub_i32 s100, s33, s34
	s_mul_hi_i32 s101, s100, 0x1640
	s_mul_i32 s100, s100, 0x1640
	s_branch .Lpf_load_2159
